# t1 + non-slack CUs delay their in-proj start by ~4us (s_sleep) to de-phase epilogue store bursts
# speedup vs baseline: 1.0083x; 1.0002x over previous
; #define PG8_STAGE(bufoff, gbase, voff) do { _Pragma("unroll") for (int _i = 0; _i < 2; ++_i) \
;         __builtin_amdgcn_global_load_lds((const unsigned*)((const char*)(gbase) + (voff)[_i]), (LAS unsigned*)(lds + (bufoff) + ldsw + _i * 8192), 16, 0, 0); } while (0)
; #define PG8_BAR __builtin_amdgcn_s_barrier()
; template <class Epi, class Sched>
; __device__ __forceinline__ void gemm_phase(LAS unsigned char* lds, const Gemm g, const Sched& S, const Epi& E, const int tid) {
;     ...
;     for (int i = 0; i < 2; ++i) { int R, C; stage_rc(tid * 16 + i * 8192, R, C); const int Rb = Epi::PERM ? ((R & ~31) + perm32(R & 31)) : R;
;         voffA[i] = (unsigned)(R * g.lda + C) * 2u; voffB[i] = (unsigned)(Rb * g.ldb + C) * 2u; }
;     const size_t kstep = (size_t)(BK * 2);
;     const size_t hstepA = (size_t)HALF * g.lda * 2, hstepB = (size_t)HALF * g.ldb * 2;
;     const size_t tstepA = 2 * hstepA, tstepB = 2 * hstepB;
;     const unsigned ldsw = (unsigned)wid * 1024u;
;     const int aoff = lds_byte(wr * 64 + fr, fq * 8), boff = lds_byte(wc * 32 + fr, fq * 8);
;     ...
;     const char* cA = (const char*)g.A + (size_t)cur.pm * tstepA; const char* cB = (const char*)g.Bt + (size_t)cur.pn * tstepB;
;     PG8_STAGE(PG8_SB(0, 0), cB, voffB); PG8_STAGE(PG8_SB(0, 1), cB + hstepB, voffB); PG8_STAGE(PG8_SA(0, 0), cA, voffA); PG8_STAGE(PG8_SA(0, 1), cA + hstepA, voffA);
;     if (wr == 1) PG8_BAR;
.LBB0_338:
	s_andn2_b64 vcc, exec, s[0:1]
	s_cbranch_vccnz .LBB0_25
	v_ashrrev_i32_e32 v2, 31, v4
	v_lshrrev_b32_e32 v2, 22, v2
	v_add_u32_e32 v2, v4, v2
	v_and_b32_e32 v2, 0xfffffc00, v2
	v_sub_u32_e32 v2, v4, v2
	v_lshrrev_b32_e32 v3, 4, v2
	v_bitop3_b32 v3, v3, v2, 32 bitop3:0x6c
	v_ashrrev_i32_e32 v2, 31, v2
	v_lshrrev_b32_e32 v1, 26, v1
	v_lshrrev_b32_e32 v2, 26, v2
	v_add_u32_e32 v1, v0, v1
	v_add_u32_e32 v2, v3, v2
	v_ashrrev_i32_e32 v1, 6, v1
	v_ashrrev_i32_e32 v10, 6, v2
	v_lshlrev_b32_e32 v5, 3, v1
	v_mul_i32_i24_e32 v6, 64, v10
	v_and_b32_e32 v5, -16, v5
	v_sub_u32_e32 v3, v3, v6
	v_add_u32_e32 v2, v10, v5
	v_lshlrev_b32_e32 v5, 5, v1
	v_ashrrev_i16_sdwa v3, v226, sext(v3) dst_sel:DWORD dst_unused:UNUSED_PAD src0_sel:DWORD src1_sel:BYTE_0
	v_and_b32_e32 v5, 32, v5
	v_bfe_i32 v11, v3, 0, 16
	v_lshlrev_b32_e32 v3, 1, v2
	v_lshrrev_b32_e32 v6, 2, v2
	v_and_b32_e32 v7, 3, v10
	s_mov_b32 s0, 0xfffe0
	v_and_b32_e32 v3, 24, v3
	v_and_b32_e32 v6, 4, v6
	v_and_or_b32 v7, v2, s0, v7
	v_add_lshl_u32 v5, v5, v11, 1
	v_or3_b32 v3, v7, v6, v3
	v_lshl_add_u32 v144, v2, 12, v5
	v_add_u32_e32 v2, 0x2000, v4
	v_lshl_add_u32 v192, v3, 12, v5
	v_ashrrev_i32_e32 v3, 31, v2
	v_lshrrev_b32_e32 v3, 22, v3
	v_add_u32_e32 v3, v2, v3
	v_ashrrev_i32_e32 v12, 10, v3
	v_mul_i32_i24_e32 v3, 0x400, v12
	v_sub_u32_e32 v2, v2, v3
	v_lshrrev_b32_e32 v3, 4, v2
	v_bitop3_b32 v2, v3, v2, 32 bitop3:0x6c
	v_ashrrev_i32_e32 v4, 31, v2
	v_lshrrev_b32_e32 v4, 26, v4
	v_lshlrev_b32_e32 v3, 3, v12
	v_add_u32_e32 v4, v2, v4
	s_add_u32 s10, s74, s4
	v_and_b32_e32 v3, -16, v3
	v_ashrrev_i32_e32 v13, 6, v4
	s_addc_u32 s11, s75, 0
	s_ashr_i32 s4, s8, 6
	v_add_u32_e32 v3, v13, v3
	v_and_b32_e32 v6, 3, v13
	v_and_or_b32 v6, v3, s0, v6
	s_ashr_i32 s15, s8, 8
	s_lshl_b32 s25, s4, 10
	v_readlane_b32 s0, v251, 56
	v_readlane_b32 s1, v251, 57
	s_mov_b32 s2, s0
	s_add_u32 s27, s10, 0x16000000
	s_mul_i32 s1, s2, 0x4600000
	s_addc_u32 s28, s11, 0
	s_mul_hi_i32 s0, s0, 0x4600000
	s_add_u32 s50, s10, s1
	v_and_b32_e32 v4, 0xc0, v4
	s_addc_u32 s51, s11, s0
	s_ashr_i32 s45, s44, 31
	s_ashr_i32 s47, s46, 31
	v_sub_u32_e32 v2, v2, v4
	s_lshl_b64 s[0:1], s[44:45], 20
	s_lshl_b64 s[2:3], s[46:47], 20
	v_ashrrev_i16_sdwa v2, v226, sext(v2) dst_sel:DWORD dst_unused:UNUSED_PAD src0_sel:DWORD src1_sel:BYTE_0
	s_add_u32 s38, s50, s2
	v_lshlrev_b32_e32 v5, 5, v12
	v_bfe_i32 v14, v2, 0, 16
	v_lshlrev_b32_e32 v2, 1, v3
	v_lshrrev_b32_e32 v4, 2, v3
	s_addc_u32 s39, s51, s3
	s_add_i32 s45, s25, 0
	s_cmp_ge_u32 s68, 0x80
	s_cbranch_scc1 .Lstg_skip
	s_sleep 94
.Lstg_skip:
	v_and_b32_e32 v5, 32, v5
	v_and_b32_e32 v2, 24, v2
	v_and_b32_e32 v4, 4, v4
	s_add_i32 m0, s45, 0x10000
	v_or3_b32 v2, v6, v4, v2
	v_add_lshl_u32 v4, v5, v14, 1
	global_load_lds_dwordx4 v192, s[38:39]
	s_add_i32 m0, s45, 0x12000
	v_lshl_add_u32 v148, v2, 12, v4
	s_add_u32 s2, s38, 0x80000
	global_load_lds_dwordx4 v148, s[38:39]
	s_addc_u32 s3, s39, 0
	s_add_i32 m0, s45, 0x14000
	v_lshl_add_u32 v146, v3, 12, v4
	global_load_lds_dwordx4 v192, s[2:3]
	s_add_i32 m0, s45, 0x16000
	v_mov_b32_e32 v149, v193
	global_load_lds_dwordx4 v148, s[2:3]
	s_add_u32 s2, s27, s0
	s_addc_u32 s3, s28, s1
	s_add_i32 s47, s45, 0x2000
	s_mov_b32 m0, s45
	s_add_u32 s0, s2, 0x80000
	global_load_lds_dwordx4 v144, s[2:3]
	s_mov_b32 m0, s47
	s_addc_u32 s1, s3, 0
	s_add_i32 s52, s45, 0x4000
	global_load_lds_dwordx4 v146, s[2:3]
	s_mov_b32 m0, s52
	s_add_i32 s53, s45, 0x6000
	global_load_lds_dwordx4 v144, s[0:1]
	s_mov_b32 m0, s53
	v_mov_b32_e32 v145, v193
	global_load_lds_dwordx4 v146, s[0:1]
	v_mov_b32_e32 v147, v193
	s_cmp_eq_u32 s15, 1
	v_lshl_add_u64 v[8:9], s[38:39], 0, v[192:193]
	v_lshl_add_u64 v[6:7], s[38:39], 0, v[148:149]
	v_lshl_add_u64 v[2:3], s[2:3], 0, v[144:145]
	s_cselect_b64 s[0:1], -1, 0
	s_cmp_lg_u32 s15, 1
	v_lshl_add_u64 v[4:5], s[2:3], 0, v[146:147]
	s_cbranch_scc1 .LBB0_341
	s_barrier
